# v30 plus the in-projection GEMM K-loop head pinned to a 64-byte boundary (.p2align 6)
# speedup vs baseline: 1.0005x; 1.0005x over previous
; template <class Epi, class Sched, bool ALIGN_EPI = false, bool SP2 = false, bool TWOA = false, bool AGM = false>
; __device__ __forceinline__ void gemm_phase(LAS unsigned char* lds, const Gemm g, const Sched& S, const Epi& E, int wid) {
;     ...
;         const bool has_next = S.next(ui + 1, nxt);
;         const char* nA = has_next ? (const char*)g.A + (size_t)nxt.pm * tstepA : cA; const char* nB = has_next ? (const char*)g.Bt + (size_t)nxt.pn * tstep : cB;
;         for (int t = 0; t < nt; t += 2) {
;             const bool last = (t == nt - 2);
;             const char* cA2 = TWOA ? (const char*)g.A2 + (cA - (const char*)g.A) - (size_t)nh * kstepA : cA;
;             const char* a1_ = (TWOA && t + 1 >= nh ? cA2 : cA) + (size_t)(t + 1) * kstepA;
;             const char* a2_ = last ? nA : (TWOA && t + 2 >= nh ? cA2 : cA) + (size_t)(t + 2) * kstepA; const char* a1 = a1_; const char* a2 = a2_; const char* b2 = last ? nB : cB + (size_t)(t + 2) * kstep;
;     ...
;         for (int a = 0; a < 2; ++a)
; #pragma unroll
;             for (int b = 0; b < 2; ++b)
; #pragma unroll
;                 for (int m = 0; m < 4; ++m)
; #pragma unroll
;                     for (int n = 0; n < 2; ++n) acc[a][b][m][n] = (f32x4){0.f, 0.f, 0.f, 0.f};
.LBB0_229:
	s_ashr_i32 s55, s54, 31
	s_lshl_b64 s[34:35], s[54:55], 21
	s_add_u32 s56, s58, s34
	s_addc_u32 s57, s59, s35
	s_and_b64 s[34:35], s[4:5], exec
	s_cselect_b32 s7, s57, s11
	s_cselect_b32 s9, s56, s10
	s_ashr_i32 s53, s52, 31
	s_lshl_b64 s[34:35], s[52:53], 21
	s_add_u32 s64, s3, s34
	s_addc_u32 s65, s74, s35
	s_and_b64 s[34:35], s[4:5], exec
	s_cselect_b32 s53, s65, s13
	s_cselect_b32 s55, s64, s12
	s_add_u32 s10, s10, 0x100080
	s_addc_u32 s11, s11, 0
	s_add_u32 s68, s12, 0x100
	v_mov_b32_e32 v0, 0
	s_addc_u32 s69, s13, 0
	s_mov_b32 s70, -2
	v_mov_b32_e32 v1, v0
	v_mov_b32_e32 v2, v0
	v_mov_b32_e32 v3, v0
	v_mov_b32_e32 v4, v0
	v_mov_b32_e32 v5, v0
	v_mov_b32_e32 v6, v0
	v_mov_b32_e32 v7, v0
	v_mov_b32_e32 v16, v0
	v_mov_b32_e32 v17, v0
	v_mov_b32_e32 v18, v0
	v_mov_b32_e32 v19, v0
	v_mov_b32_e32 v20, v0
	v_mov_b32_e32 v21, v0
	v_mov_b32_e32 v22, v0
	v_mov_b32_e32 v23, v0
	v_mov_b32_e32 v32, v0
	v_mov_b32_e32 v33, v0
	v_mov_b32_e32 v34, v0
	v_mov_b32_e32 v35, v0
	v_mov_b32_e32 v36, v0
	v_mov_b32_e32 v37, v0
	v_mov_b32_e32 v38, v0
	v_mov_b32_e32 v39, v0
	v_mov_b32_e32 v48, v0
	v_mov_b32_e32 v49, v0
	v_mov_b32_e32 v50, v0
	v_mov_b32_e32 v51, v0
	v_mov_b32_e32 v52, v0
	v_mov_b32_e32 v53, v0
	v_mov_b32_e32 v54, v0
	v_mov_b32_e32 v55, v0
	v_mov_b32_e32 v8, v0
	s_waitcnt lgkmcnt(0)
	v_mov_b32_e32 v9, v0
	v_mov_b32_e32 v10, v0
	v_mov_b32_e32 v11, v0
	v_mov_b32_e32 v12, v0
	v_mov_b32_e32 v13, v0
	v_mov_b32_e32 v14, v0
	v_mov_b32_e32 v15, v0
	v_mov_b32_e32 v24, v0
	v_mov_b32_e32 v25, v0
	v_mov_b32_e32 v26, v0
	v_mov_b32_e32 v27, v0
	v_mov_b32_e32 v28, v0
	v_mov_b32_e32 v29, v0
	v_mov_b32_e32 v30, v0
	v_mov_b32_e32 v31, v0
	v_mov_b32_e32 v40, v0
	v_mov_b32_e32 v41, v0
	v_mov_b32_e32 v42, v0
	v_mov_b32_e32 v43, v0
	v_mov_b32_e32 v44, v0
	v_mov_b32_e32 v45, v0
	v_mov_b32_e32 v46, v0
	v_mov_b32_e32 v47, v0
	v_mov_b32_e32 v56, v0
	v_mov_b32_e32 v57, v0
	v_mov_b32_e32 v58, v0
	v_mov_b32_e32 v59, v0
	v_mov_b32_e32 v60, v0
	v_mov_b32_e32 v61, v0
	v_mov_b32_e32 v62, v0
	v_mov_b32_e32 v63, v0
	v_mov_b32_e32 v64, v0
	v_mov_b32_e32 v65, v0
	v_mov_b32_e32 v66, v0
	v_mov_b32_e32 v67, v0
	v_mov_b32_e32 v68, v0
	v_mov_b32_e32 v69, v0
	v_mov_b32_e32 v70, v0
	v_mov_b32_e32 v71, v0
	v_mov_b32_e32 v80, v0
	v_mov_b32_e32 v81, v0
	v_mov_b32_e32 v82, v0
	v_mov_b32_e32 v83, v0
	v_mov_b32_e32 v84, v0
	v_mov_b32_e32 v85, v0
	v_mov_b32_e32 v86, v0
	v_mov_b32_e32 v87, v0
	v_mov_b32_e32 v96, v0
	v_mov_b32_e32 v97, v0
	v_mov_b32_e32 v98, v0
	v_mov_b32_e32 v99, v0
	v_mov_b32_e32 v100, v0
	v_mov_b32_e32 v101, v0
	v_mov_b32_e32 v102, v0
	v_mov_b32_e32 v103, v0
	v_mov_b32_e32 v112, v0
	v_mov_b32_e32 v113, v0
	v_mov_b32_e32 v114, v0
	v_mov_b32_e32 v115, v0
	v_mov_b32_e32 v116, v0
	v_mov_b32_e32 v117, v0
	v_mov_b32_e32 v118, v0
	v_mov_b32_e32 v119, v0
	v_mov_b32_e32 v72, v0
	v_mov_b32_e32 v73, v0
	v_mov_b32_e32 v74, v0
	v_mov_b32_e32 v75, v0
	v_mov_b32_e32 v76, v0
	v_mov_b32_e32 v77, v0
	v_mov_b32_e32 v78, v0
	v_mov_b32_e32 v79, v0
	v_mov_b32_e32 v88, v0
	v_mov_b32_e32 v89, v0
	v_mov_b32_e32 v90, v0
	v_mov_b32_e32 v91, v0
	v_mov_b32_e32 v92, v0
	v_mov_b32_e32 v93, v0
	v_mov_b32_e32 v94, v0
	v_mov_b32_e32 v95, v0
	v_mov_b32_e32 v104, v0
	v_mov_b32_e32 v105, v0
	v_mov_b32_e32 v106, v0
	v_mov_b32_e32 v107, v0
	v_mov_b32_e32 v108, v0
	v_mov_b32_e32 v109, v0
	v_mov_b32_e32 v110, v0
	v_mov_b32_e32 v111, v0
	v_mov_b32_e32 v120, v0
	v_mov_b32_e32 v121, v0
	v_mov_b32_e32 v122, v0
	v_mov_b32_e32 v123, v0
	v_mov_b32_e32 v124, v0
	v_mov_b32_e32 v125, v0
	v_mov_b32_e32 v126, v0
	v_mov_b32_e32 v127, v0
	.p2align	6
